# swiglu epilogues (FFN1/FFN2): 8-wide batched mul/exp/add/rcp/mul schedule instead of 2-wide dependent chains; same math, bit-identical
# baseline (speedup 1.0000x reference)
; __device__ __forceinline__ unsigned cvt_pk_bf16(float lo, float hi) { f32x2 v = {lo, hi}; bf16x2_t b = __builtin_convertvector(v, bf16x2_t); return __builtin_bit_cast(unsigned, b); }
; __device__ __forceinline__ float fast_exp2(float x) { return __builtin_amdgcn_exp2f(x); }
; __device__ __forceinline__ float fast_rcp(float x) { return __builtin_amdgcn_rcpf(x); }
;     __device__ __forceinline__ void operator()(ACC_T, const Unit& u, int wr, int wc, int fr, int fq) const {
;     ...
;             for (int m = 0; m < 4; ++m) { bf16_t* rowp = Hp + (size_t)(row0 + ai * HALF + m * 16) * DFF + col0; float r[8];
; #pragma unroll
;                 for (int n = 0; n < 2; ++n)
; #pragma unroll
;                     for (int e = 0; e < 4; ++e) { const float g = acc[ai][0][m][n][e], up = acc[ai][1][m][n][e]; r[n * 4 + e] = g * fast_rcp(1.f + fast_exp2(-g * LOG2E)) * up; }
;                 u32x4 w; w.x = cvt_pk_bf16(r[0], r[1]); w.y = cvt_pk_bf16(r[2], r[3]); w.z = cvt_pk_bf16(r[4], r[5]); w.w = cvt_pk_bf16(r[6], r[7]);
;                 *(u32x4*)rowp = w; }
.LBB0_125:
	v_lshl_or_b32 v156, s2, 7, v159
	s_mul_i32 s2, s3, 0x1c0000
	s_mul_hi_i32 s7, s3, 0x1c0000
	v_readlane_b32 s14, v251, 56
	v_readlane_b32 s15, v251, 57
	v_ashrrev_i32_e32 v157, 31, v156
	s_add_u32 s2, s14, s2
	s_addc_u32 s3, s15, s7
	v_lshl_add_u64 v[156:157], v[156:157], 1, s[2:3]
	s_andn2_b64 vcc, exec, s[36:37]
	s_mov_b64 s[14:15], -1
	v_lshl_add_u64 v[186:187], v[156:157], 0, v[136:137]
	v_mul_f32_e32 v162, 0xbfb8aa3b, v126
	v_mul_f32_e32 v163, 0xbfb8aa3b, v127
	v_mul_f32_e32 v164, 0xbfb8aa3b, v128
	v_mul_f32_e32 v165, 0xbfb8aa3b, v129
	v_mul_f32_e32 v166, 0xbfb8aa3b, v122
	v_mul_f32_e32 v167, 0xbfb8aa3b, v123
	v_mul_f32_e32 v168, 0xbfb8aa3b, v124
	v_mul_f32_e32 v169, 0xbfb8aa3b, v125
	v_exp_f32_e32 v162, v162
	v_exp_f32_e32 v163, v163
	v_exp_f32_e32 v164, v164
	v_exp_f32_e32 v165, v165
	v_exp_f32_e32 v166, v166
	v_exp_f32_e32 v167, v167
	v_exp_f32_e32 v168, v168
	v_exp_f32_e32 v169, v169
	v_add_f32_e32 v162, 1.0, v162
	v_add_f32_e32 v163, 1.0, v163
	v_add_f32_e32 v164, 1.0, v164
	v_add_f32_e32 v165, 1.0, v165
	v_add_f32_e32 v166, 1.0, v166
	v_add_f32_e32 v167, 1.0, v167
	v_add_f32_e32 v168, 1.0, v168
	v_add_f32_e32 v169, 1.0, v169
	v_rcp_f32_e32 v162, v162
	v_rcp_f32_e32 v163, v163
	v_rcp_f32_e32 v164, v164
	v_rcp_f32_e32 v165, v165
	v_rcp_f32_e32 v166, v166
	v_rcp_f32_e32 v167, v167
	v_rcp_f32_e32 v168, v168
	v_rcp_f32_e32 v169, v169
	v_mul_f32_e32 v126, v126, v162
	v_mul_f32_e32 v127, v127, v163
	v_mul_f32_e32 v128, v128, v164
	v_mul_f32_e32 v129, v129, v165
	v_mul_f32_e32 v122, v122, v166
	v_mul_f32_e32 v123, v123, v167
	v_mul_f32_e32 v124, v124, v168
	v_mul_f32_e32 v125, v125, v169
	v_mul_f32_e32 v118, v126, v118
	v_mul_f32_e32 v119, v127, v119
	v_mul_f32_e32 v120, v128, v120
	v_mul_f32_e32 v121, v129, v121
	v_mul_f32_e32 v114, v122, v114
	v_mul_f32_e32 v115, v123, v115
	v_mul_f32_e32 v116, v124, v116
	v_mul_f32_e32 v117, v125, v117
	v_cvt_pk_bf16_f32 v178, v118, v119
	v_cvt_pk_bf16_f32 v179, v120, v121
	v_cvt_pk_bf16_f32 v180, v114, v115
	v_cvt_pk_bf16_f32 v181, v116, v117
	global_store_dwordx4 v[186:187], v[178:181], off
	v_lshl_add_u64 v[188:189], v[156:157], 0, v[138:139]
	v_mul_f32_e32 v170, 0xbfb8aa3b, v110
	v_mul_f32_e32 v171, 0xbfb8aa3b, v111
	v_mul_f32_e32 v172, 0xbfb8aa3b, v112
	v_mul_f32_e32 v173, 0xbfb8aa3b, v113
	v_mul_f32_e32 v174, 0xbfb8aa3b, v106
	v_mul_f32_e32 v175, 0xbfb8aa3b, v107
	v_mul_f32_e32 v176, 0xbfb8aa3b, v108
	v_mul_f32_e32 v177, 0xbfb8aa3b, v109
	v_exp_f32_e32 v170, v170
	v_exp_f32_e32 v171, v171
	v_exp_f32_e32 v172, v172
	v_exp_f32_e32 v173, v173
	v_exp_f32_e32 v174, v174
	v_exp_f32_e32 v175, v175
	v_exp_f32_e32 v176, v176
	v_exp_f32_e32 v177, v177
	v_add_f32_e32 v170, 1.0, v170
	v_add_f32_e32 v171, 1.0, v171
	v_add_f32_e32 v172, 1.0, v172
	v_add_f32_e32 v173, 1.0, v173
	v_add_f32_e32 v174, 1.0, v174
	v_add_f32_e32 v175, 1.0, v175
	v_add_f32_e32 v176, 1.0, v176
	v_add_f32_e32 v177, 1.0, v177
	v_rcp_f32_e32 v170, v170
	v_rcp_f32_e32 v171, v171
	v_rcp_f32_e32 v172, v172
	v_rcp_f32_e32 v173, v173
	v_rcp_f32_e32 v174, v174
	v_rcp_f32_e32 v175, v175
	v_rcp_f32_e32 v176, v176
	v_rcp_f32_e32 v177, v177
	v_mul_f32_e32 v110, v110, v170
	v_mul_f32_e32 v111, v111, v171
	v_mul_f32_e32 v112, v112, v172
	v_mul_f32_e32 v113, v113, v173
	v_mul_f32_e32 v106, v106, v174
	v_mul_f32_e32 v107, v107, v175
	v_mul_f32_e32 v108, v108, v176
	v_mul_f32_e32 v109, v109, v177
	v_mul_f32_e32 v102, v110, v102
	v_mul_f32_e32 v103, v111, v103
	v_mul_f32_e32 v104, v112, v104
	v_mul_f32_e32 v105, v113, v105
	v_mul_f32_e32 v98, v106, v98
	v_mul_f32_e32 v99, v107, v99
	v_mul_f32_e32 v100, v108, v100
	v_mul_f32_e32 v101, v109, v101
	v_cvt_pk_bf16_f32 v182, v102, v103
	v_cvt_pk_bf16_f32 v183, v104, v105
	v_cvt_pk_bf16_f32 v184, v98, v99
	v_cvt_pk_bf16_f32 v185, v100, v101
	global_store_dwordx4 v[188:189], v[182:185], off
	v_lshl_add_u64 v[186:187], v[156:157], 0, v[140:141]
	v_mul_f32_e32 v162, 0xbfb8aa3b, v94
	v_mul_f32_e32 v163, 0xbfb8aa3b, v95
	v_mul_f32_e32 v164, 0xbfb8aa3b, v96
	v_mul_f32_e32 v165, 0xbfb8aa3b, v97
	v_mul_f32_e32 v166, 0xbfb8aa3b, v90
	v_mul_f32_e32 v167, 0xbfb8aa3b, v91
	v_mul_f32_e32 v168, 0xbfb8aa3b, v92
	v_mul_f32_e32 v169, 0xbfb8aa3b, v93
	v_exp_f32_e32 v162, v162
	v_exp_f32_e32 v163, v163
	v_exp_f32_e32 v164, v164
	v_exp_f32_e32 v165, v165
	v_exp_f32_e32 v166, v166
	v_exp_f32_e32 v167, v167
	v_exp_f32_e32 v168, v168
	v_exp_f32_e32 v169, v169
	v_add_f32_e32 v162, 1.0, v162
	v_add_f32_e32 v163, 1.0, v163
	v_add_f32_e32 v164, 1.0, v164
	v_add_f32_e32 v165, 1.0, v165
	v_add_f32_e32 v166, 1.0, v166
	v_add_f32_e32 v167, 1.0, v167
	v_add_f32_e32 v168, 1.0, v168
	v_add_f32_e32 v169, 1.0, v169
	v_rcp_f32_e32 v162, v162
	v_rcp_f32_e32 v163, v163
	v_rcp_f32_e32 v164, v164
	v_rcp_f32_e32 v165, v165
	v_rcp_f32_e32 v166, v166
	v_rcp_f32_e32 v167, v167
	v_rcp_f32_e32 v168, v168
	v_rcp_f32_e32 v169, v169
	v_mul_f32_e32 v94, v94, v162
	v_mul_f32_e32 v95, v95, v163
	v_mul_f32_e32 v96, v96, v164
	v_mul_f32_e32 v97, v97, v165
	v_mul_f32_e32 v90, v90, v166
	v_mul_f32_e32 v91, v91, v167
	v_mul_f32_e32 v92, v92, v168
	v_mul_f32_e32 v93, v93, v169
	v_mul_f32_e32 v86, v94, v86
	v_mul_f32_e32 v87, v95, v87
	v_mul_f32_e32 v88, v96, v88
	v_mul_f32_e32 v89, v97, v89
	v_mul_f32_e32 v82, v90, v82
	v_mul_f32_e32 v83, v91, v83
	v_mul_f32_e32 v84, v92, v84
	v_mul_f32_e32 v85, v93, v85
	v_cvt_pk_bf16_f32 v178, v86, v87
	v_cvt_pk_bf16_f32 v179, v88, v89
	v_cvt_pk_bf16_f32 v180, v82, v83
	v_cvt_pk_bf16_f32 v181, v84, v85
	global_store_dwordx4 v[186:187], v[178:181], off
	v_lshl_add_u64 v[188:189], v[156:157], 0, v[142:143]
	v_mul_f32_e32 v170, 0xbfb8aa3b, v78
	v_mul_f32_e32 v171, 0xbfb8aa3b, v79
	v_mul_f32_e32 v172, 0xbfb8aa3b, v80
; __device__ __forceinline__ unsigned cvt_pk_bf16(float lo, float hi) { f32x2 v = {lo, hi}; bf16x2_t b = __builtin_convertvector(v, bf16x2_t); return __builtin_bit_cast(unsigned, b); }
; __device__ __forceinline__ float fast_exp2(float x) { return __builtin_amdgcn_exp2f(x); }
; __device__ __forceinline__ float fast_rcp(float x) { return __builtin_amdgcn_rcpf(x); }
;     __device__ __forceinline__ void operator()(ACC_T, const Unit& u, int wr, int wc, int fr, int fq) const {
;     ...
;             for (int m = 0; m < 4; ++m) { bf16_t* rowp = Hp + (size_t)(row0 + ai * HALF + m * 16) * DFF + col0; float r[8];
; #pragma unroll
;                 for (int n = 0; n < 2; ++n)
; #pragma unroll
;                     for (int e = 0; e < 4; ++e) { const float g = acc[ai][0][m][n][e], up = acc[ai][1][m][n][e]; r[n * 4 + e] = g * fast_rcp(1.f + fast_exp2(-g * LOG2E)) * up; }
;                 u32x4 w; w.x = cvt_pk_bf16(r[0], r[1]); w.y = cvt_pk_bf16(r[2], r[3]); w.z = cvt_pk_bf16(r[4], r[5]); w.w = cvt_pk_bf16(r[6], r[7]);
;                 *(u32x4*)rowp = w; }
	v_mul_f32_e32 v173, 0xbfb8aa3b, v81
	v_mul_f32_e32 v174, 0xbfb8aa3b, v74
	v_mul_f32_e32 v175, 0xbfb8aa3b, v75
	v_mul_f32_e32 v176, 0xbfb8aa3b, v76
	v_mul_f32_e32 v177, 0xbfb8aa3b, v77
	v_exp_f32_e32 v170, v170
	v_exp_f32_e32 v171, v171
	v_exp_f32_e32 v172, v172
	v_exp_f32_e32 v173, v173
	v_exp_f32_e32 v174, v174
	v_exp_f32_e32 v175, v175
	v_exp_f32_e32 v176, v176
	v_exp_f32_e32 v177, v177
	v_add_f32_e32 v170, 1.0, v170
	v_add_f32_e32 v171, 1.0, v171
	v_add_f32_e32 v172, 1.0, v172
	v_add_f32_e32 v173, 1.0, v173
	v_add_f32_e32 v174, 1.0, v174
	v_add_f32_e32 v175, 1.0, v175
	v_add_f32_e32 v176, 1.0, v176
	v_add_f32_e32 v177, 1.0, v177
	v_rcp_f32_e32 v170, v170
	v_rcp_f32_e32 v171, v171
	v_rcp_f32_e32 v172, v172
	v_rcp_f32_e32 v173, v173
	v_rcp_f32_e32 v174, v174
	v_rcp_f32_e32 v175, v175
	v_rcp_f32_e32 v176, v176
	v_rcp_f32_e32 v177, v177
	v_mul_f32_e32 v78, v78, v170
	v_mul_f32_e32 v79, v79, v171
	v_mul_f32_e32 v80, v80, v172
	v_mul_f32_e32 v81, v81, v173
	v_mul_f32_e32 v74, v74, v174
	v_mul_f32_e32 v75, v75, v175
	v_mul_f32_e32 v76, v76, v176
	v_mul_f32_e32 v77, v77, v177
	v_mul_f32_e32 v70, v78, v70
	v_mul_f32_e32 v71, v79, v71
	v_mul_f32_e32 v72, v80, v72
	v_mul_f32_e32 v73, v81, v73
	v_mul_f32_e32 v66, v74, v66
	v_mul_f32_e32 v67, v75, v67
	v_mul_f32_e32 v68, v76, v68
	v_mul_f32_e32 v69, v77, v69
	v_cvt_pk_bf16_f32 v182, v70, v71
	v_cvt_pk_bf16_f32 v183, v72, v73
	v_cvt_pk_bf16_f32 v184, v66, v67
	v_cvt_pk_bf16_f32 v185, v68, v69
	global_store_dwordx4 v[188:189], v[182:185], off
	v_lshl_add_u64 v[186:187], v[156:157], 0, v[144:145]
	v_mul_f32_e32 v162, 0xbfb8aa3b, v62
	v_mul_f32_e32 v163, 0xbfb8aa3b, v63
	v_mul_f32_e32 v164, 0xbfb8aa3b, v64
	v_mul_f32_e32 v165, 0xbfb8aa3b, v65
	v_mul_f32_e32 v166, 0xbfb8aa3b, v58
	v_mul_f32_e32 v167, 0xbfb8aa3b, v59
	v_mul_f32_e32 v168, 0xbfb8aa3b, v60
	v_mul_f32_e32 v169, 0xbfb8aa3b, v61
	v_exp_f32_e32 v162, v162
	v_exp_f32_e32 v163, v163
	v_exp_f32_e32 v164, v164
	v_exp_f32_e32 v165, v165
	v_exp_f32_e32 v166, v166
	v_exp_f32_e32 v167, v167
	v_exp_f32_e32 v168, v168
	v_exp_f32_e32 v169, v169
	v_add_f32_e32 v162, 1.0, v162
	v_add_f32_e32 v163, 1.0, v163
	v_add_f32_e32 v164, 1.0, v164
	v_add_f32_e32 v165, 1.0, v165
	v_add_f32_e32 v166, 1.0, v166
	v_add_f32_e32 v167, 1.0, v167
	v_add_f32_e32 v168, 1.0, v168
	v_add_f32_e32 v169, 1.0, v169
	v_rcp_f32_e32 v162, v162
	v_rcp_f32_e32 v163, v163
	v_rcp_f32_e32 v164, v164
	v_rcp_f32_e32 v165, v165
	v_rcp_f32_e32 v166, v166
	v_rcp_f32_e32 v167, v167
	v_rcp_f32_e32 v168, v168
	v_rcp_f32_e32 v169, v169
	v_mul_f32_e32 v62, v62, v162
	v_mul_f32_e32 v63, v63, v163
	v_mul_f32_e32 v64, v64, v164
	v_mul_f32_e32 v65, v65, v165
	v_mul_f32_e32 v58, v58, v166
	v_mul_f32_e32 v59, v59, v167
	v_mul_f32_e32 v60, v60, v168
	v_mul_f32_e32 v61, v61, v169
	v_mul_f32_e32 v54, v62, v54
	v_mul_f32_e32 v55, v63, v55
	v_mul_f32_e32 v56, v64, v56
	v_mul_f32_e32 v57, v65, v57
	v_mul_f32_e32 v50, v58, v50
	v_mul_f32_e32 v51, v59, v51
	v_mul_f32_e32 v52, v60, v52
	v_mul_f32_e32 v53, v61, v53
	v_cvt_pk_bf16_f32 v178, v54, v55
	v_cvt_pk_bf16_f32 v179, v56, v57
	v_cvt_pk_bf16_f32 v180, v50, v51
	v_cvt_pk_bf16_f32 v181, v52, v53
	global_store_dwordx4 v[186:187], v[178:181], off
	v_lshl_add_u64 v[188:189], v[156:157], 0, v[146:147]
	v_mul_f32_e32 v170, 0xbfb8aa3b, v46
	v_mul_f32_e32 v171, 0xbfb8aa3b, v47
	v_mul_f32_e32 v172, 0xbfb8aa3b, v48
	v_mul_f32_e32 v173, 0xbfb8aa3b, v49
	v_mul_f32_e32 v174, 0xbfb8aa3b, v42
	v_mul_f32_e32 v175, 0xbfb8aa3b, v43
	v_mul_f32_e32 v176, 0xbfb8aa3b, v44
	v_mul_f32_e32 v177, 0xbfb8aa3b, v45
	v_exp_f32_e32 v170, v170
	v_exp_f32_e32 v171, v171
	v_exp_f32_e32 v172, v172
	v_exp_f32_e32 v173, v173
	v_exp_f32_e32 v174, v174
	v_exp_f32_e32 v175, v175
	v_exp_f32_e32 v176, v176
	v_exp_f32_e32 v177, v177
	v_add_f32_e32 v170, 1.0, v170
	v_add_f32_e32 v171, 1.0, v171
	v_add_f32_e32 v172, 1.0, v172
	v_add_f32_e32 v173, 1.0, v173
	v_add_f32_e32 v174, 1.0, v174
	v_add_f32_e32 v175, 1.0, v175
	v_add_f32_e32 v176, 1.0, v176
	v_add_f32_e32 v177, 1.0, v177
	v_rcp_f32_e32 v170, v170
	v_rcp_f32_e32 v171, v171
	v_rcp_f32_e32 v172, v172
	v_rcp_f32_e32 v173, v173
	v_rcp_f32_e32 v174, v174
	v_rcp_f32_e32 v175, v175
; __device__ __forceinline__ unsigned cvt_pk_bf16(float lo, float hi) { f32x2 v = {lo, hi}; bf16x2_t b = __builtin_convertvector(v, bf16x2_t); return __builtin_bit_cast(unsigned, b); }
; __device__ __forceinline__ float fast_exp2(float x) { return __builtin_amdgcn_exp2f(x); }
; __device__ __forceinline__ float fast_rcp(float x) { return __builtin_amdgcn_rcpf(x); }
; #define PG8_BAR __builtin_amdgcn_s_barrier()
;     __device__ __forceinline__ void operator()(ACC_T, const Unit& u, int wr, int wc, int fr, int fq) const {
;     ...
;             for (int m = 0; m < 4; ++m) { bf16_t* rowp = Hp + (size_t)(row0 + ai * HALF + m * 16) * DFF + col0; float r[8];
; #pragma unroll
;                 for (int n = 0; n < 2; ++n)
; #pragma unroll
;                     for (int e = 0; e < 4; ++e) { const float g = acc[ai][0][m][n][e], up = acc[ai][1][m][n][e]; r[n * 4 + e] = g * fast_rcp(1.f + fast_exp2(-g * LOG2E)) * up; }
;                 u32x4 w; w.x = cvt_pk_bf16(r[0], r[1]); w.y = cvt_pk_bf16(r[2], r[3]); w.z = cvt_pk_bf16(r[4], r[5]); w.w = cvt_pk_bf16(r[6], r[7]);
;                 *(u32x4*)rowp = w; }
; template <class Epi, bool ALIGN_EPI, bool ASLOT = false>
; __device__ __forceinline__ void gemm_phase(LAS unsigned char* lds, const Gemm g, const Sched& S, const Epi& E) {
;     ...
;         if constexpr (ALIGN_EPI) { if (wr == 0) PG8_BAR; }
;         E(acc, cur, wr, wc, fr, fq);
;         if (!has_next) break;
; #pragma unroll
;         for (int a = 0; a < 2; ++a)
; #pragma unroll
;             for (int b = 0; b < 2; ++b)
; #pragma unroll
;                 for (int m = 0; m < 4; ++m)
; #pragma unroll
;                     for (int n = 0; n < 2; ++n) acc[a][b][m][n] = (f32x4){0.f, 0.f, 0.f, 0.f};
;         cur = nxt; cA = nA; cB = nB; ++ui;
;         if constexpr (ALIGN_EPI) { if (wr == 1) PG8_BAR; }
	v_rcp_f32_e32 v176, v176
	v_rcp_f32_e32 v177, v177
	v_mul_f32_e32 v46, v46, v170
	v_mul_f32_e32 v47, v47, v171
	v_mul_f32_e32 v48, v48, v172
	v_mul_f32_e32 v49, v49, v173
	v_mul_f32_e32 v42, v42, v174
	v_mul_f32_e32 v43, v43, v175
	v_mul_f32_e32 v44, v44, v176
	v_mul_f32_e32 v45, v45, v177
	v_mul_f32_e32 v38, v46, v38
	v_mul_f32_e32 v39, v47, v39
	v_mul_f32_e32 v40, v48, v40
	v_mul_f32_e32 v41, v49, v41
	v_mul_f32_e32 v34, v42, v34
	v_mul_f32_e32 v35, v43, v35
	v_mul_f32_e32 v36, v44, v36
	v_mul_f32_e32 v37, v45, v37
	v_cvt_pk_bf16_f32 v182, v38, v39
	v_cvt_pk_bf16_f32 v183, v40, v41
	v_cvt_pk_bf16_f32 v184, v34, v35
	v_cvt_pk_bf16_f32 v185, v36, v37
	global_store_dwordx4 v[188:189], v[182:185], off
	v_lshl_add_u64 v[186:187], v[156:157], 0, v[148:149]
	v_mul_f32_e32 v162, 0xbfb8aa3b, v30
	v_mul_f32_e32 v163, 0xbfb8aa3b, v31
	v_mul_f32_e32 v164, 0xbfb8aa3b, v32
	v_mul_f32_e32 v165, 0xbfb8aa3b, v33
	v_mul_f32_e32 v166, 0xbfb8aa3b, v26
	v_mul_f32_e32 v167, 0xbfb8aa3b, v27
	v_mul_f32_e32 v168, 0xbfb8aa3b, v28
	v_mul_f32_e32 v169, 0xbfb8aa3b, v29
	v_exp_f32_e32 v162, v162
	v_exp_f32_e32 v163, v163
	v_exp_f32_e32 v164, v164
	v_exp_f32_e32 v165, v165
	v_exp_f32_e32 v166, v166
	v_exp_f32_e32 v167, v167
	v_exp_f32_e32 v168, v168
	v_exp_f32_e32 v169, v169
	v_add_f32_e32 v162, 1.0, v162
	v_add_f32_e32 v163, 1.0, v163
	v_add_f32_e32 v164, 1.0, v164
	v_add_f32_e32 v165, 1.0, v165
	v_add_f32_e32 v166, 1.0, v166
	v_add_f32_e32 v167, 1.0, v167
	v_add_f32_e32 v168, 1.0, v168
	v_add_f32_e32 v169, 1.0, v169
	v_rcp_f32_e32 v162, v162
	v_rcp_f32_e32 v163, v163
	v_rcp_f32_e32 v164, v164
	v_rcp_f32_e32 v165, v165
	v_rcp_f32_e32 v166, v166
	v_rcp_f32_e32 v167, v167
	v_rcp_f32_e32 v168, v168
	v_rcp_f32_e32 v169, v169
	v_mul_f32_e32 v30, v30, v162
	v_mul_f32_e32 v31, v31, v163
	v_mul_f32_e32 v32, v32, v164
	v_mul_f32_e32 v33, v33, v165
	v_mul_f32_e32 v26, v26, v166
	v_mul_f32_e32 v27, v27, v167
	v_mul_f32_e32 v28, v28, v168
	v_mul_f32_e32 v29, v29, v169
	v_mul_f32_e32 v22, v30, v22
	v_mul_f32_e32 v23, v31, v23
	v_mul_f32_e32 v24, v32, v24
	v_mul_f32_e32 v25, v33, v25
	v_mul_f32_e32 v18, v26, v18
	v_mul_f32_e32 v19, v27, v19
	v_mul_f32_e32 v20, v28, v20
	v_mul_f32_e32 v21, v29, v21
	v_cvt_pk_bf16_f32 v178, v22, v23
	v_cvt_pk_bf16_f32 v179, v24, v25
	v_cvt_pk_bf16_f32 v180, v18, v19
	v_cvt_pk_bf16_f32 v181, v20, v21
	global_store_dwordx4 v[186:187], v[178:181], off
	v_lshl_add_u64 v[188:189], v[156:157], 0, v[150:151]
	v_mul_f32_e32 v170, 0xbfb8aa3b, v14
	v_mul_f32_e32 v171, 0xbfb8aa3b, v15
	v_mul_f32_e32 v172, 0xbfb8aa3b, v16
	v_mul_f32_e32 v173, 0xbfb8aa3b, v17
	v_mul_f32_e32 v174, 0xbfb8aa3b, v10
	v_mul_f32_e32 v175, 0xbfb8aa3b, v11
	v_mul_f32_e32 v176, 0xbfb8aa3b, v12
	v_mul_f32_e32 v177, 0xbfb8aa3b, v13
	v_exp_f32_e32 v170, v170
	v_exp_f32_e32 v171, v171
	v_exp_f32_e32 v172, v172
	v_exp_f32_e32 v173, v173
	v_exp_f32_e32 v174, v174
	v_exp_f32_e32 v175, v175
	v_exp_f32_e32 v176, v176
	v_exp_f32_e32 v177, v177
	v_add_f32_e32 v170, 1.0, v170
	v_add_f32_e32 v171, 1.0, v171
	v_add_f32_e32 v172, 1.0, v172
	v_add_f32_e32 v173, 1.0, v173
	v_add_f32_e32 v174, 1.0, v174
	v_add_f32_e32 v175, 1.0, v175
	v_add_f32_e32 v176, 1.0, v176
	v_add_f32_e32 v177, 1.0, v177
	v_rcp_f32_e32 v170, v170
	v_rcp_f32_e32 v171, v171
	v_rcp_f32_e32 v172, v172
	v_rcp_f32_e32 v173, v173
	v_rcp_f32_e32 v174, v174
	v_rcp_f32_e32 v175, v175
	v_rcp_f32_e32 v176, v176
	v_rcp_f32_e32 v177, v177
	v_mul_f32_e32 v14, v14, v170
	v_mul_f32_e32 v15, v15, v171
	v_mul_f32_e32 v16, v16, v172
	v_mul_f32_e32 v17, v17, v173
	v_mul_f32_e32 v10, v10, v174
	v_mul_f32_e32 v11, v11, v175
	v_mul_f32_e32 v12, v12, v176
	v_mul_f32_e32 v13, v13, v177
	v_mul_f32_e32 v6, v14, v6
	v_mul_f32_e32 v7, v15, v7
	v_mul_f32_e32 v8, v16, v8
	v_mul_f32_e32 v9, v17, v9
	v_mul_f32_e32 v2, v10, v2
	v_mul_f32_e32 v3, v11, v3
	v_mul_f32_e32 v4, v12, v4
	v_mul_f32_e32 v5, v13, v5
	v_cvt_pk_bf16_f32 v182, v6, v7
	v_cvt_pk_bf16_f32 v183, v8, v9
	v_cvt_pk_bf16_f32 v184, v2, v3
	v_cvt_pk_bf16_f32 v185, v4, v5
	global_store_dwordx4 v[188:189], v[182:185], off
	s_cbranch_vccnz .LBB0_118
	s_andn2_b64 vcc, exec, s[0:1]
	s_cbranch_vccnz .LBB0_117
	s_barrier
	s_branch .LBB0_117

; __device__ __forceinline__ unsigned cvt_pk_bf16(float lo, float hi) { f32x2 v = {lo, hi}; bf16x2_t b = __builtin_convertvector(v, bf16x2_t); return __builtin_bit_cast(unsigned, b); }
; __device__ __forceinline__ float fast_exp2(float x) { return __builtin_amdgcn_exp2f(x); }
; __device__ __forceinline__ float fast_rcp(float x) { return __builtin_amdgcn_rcpf(x); }
;     __device__ __forceinline__ void operator()(ACC_T, const Unit& u, int wr, int wc, int fr, int fq) const {
;         const int row0 = wr * 64 + fr, col0 = u.pn * HALF + wc * 32 + 8 * fq; bf16_t* Hp = H + (size_t)u.pm * (SLOTB / 2);
; #pragma unroll
;         for (int ai = 0; ai < 2; ++ai)
; #pragma unroll
;             for (int m = 0; m < 4; ++m) { bf16_t* rowp = Hp + (size_t)(row0 + ai * HALF + m * 16) * DFF + col0; float r[8];
; #pragma unroll
;                 for (int n = 0; n < 2; ++n)
; #pragma unroll
;                     for (int e = 0; e < 4; ++e) { const float g = acc[ai][0][m][n][e], up = acc[ai][1][m][n][e]; r[n * 4 + e] = g * fast_rcp(1.f + fast_exp2(-g * LOG2E)) * up; }
;                 u32x4 w; w.x = cvt_pk_bf16(r[0], r[1]); w.y = cvt_pk_bf16(r[2], r[3]); w.z = cvt_pk_bf16(r[4], r[5]); w.w = cvt_pk_bf16(r[6], r[7]);
;                 *(u32x4*)rowp = w; }
.LBB0_856:
	v_lshl_or_b32 v156, s2, 7, v159
	s_mul_i32 s2, s3, 0x1c0000
	s_mul_hi_i32 s9, s3, 0x1c0000
	v_readlane_b32 s18, v251, 56
	v_readlane_b32 s19, v251, 57
	v_ashrrev_i32_e32 v157, 31, v156
	s_add_u32 s2, s18, s2
	s_addc_u32 s3, s19, s9
	v_lshl_add_u64 v[156:157], v[156:157], 1, s[2:3]
	v_readlane_b32 s22, v254, 52
	v_readlane_b32 s23, v254, 53
	s_andn2_b64 vcc, exec, s[40:41]
	s_mov_b64 s[18:19], -1
	v_lshl_add_u64 v[186:187], v[156:157], 0, v[136:137]
	v_mul_f32_e32 v162, 0xbfb8aa3b, v126
	v_mul_f32_e32 v163, 0xbfb8aa3b, v127
	v_mul_f32_e32 v164, 0xbfb8aa3b, v128
	v_mul_f32_e32 v165, 0xbfb8aa3b, v129
	v_mul_f32_e32 v166, 0xbfb8aa3b, v122
	v_mul_f32_e32 v167, 0xbfb8aa3b, v123
	v_mul_f32_e32 v168, 0xbfb8aa3b, v124
	v_mul_f32_e32 v169, 0xbfb8aa3b, v125
	v_exp_f32_e32 v162, v162
	v_exp_f32_e32 v163, v163
	v_exp_f32_e32 v164, v164
	v_exp_f32_e32 v165, v165
	v_exp_f32_e32 v166, v166
	v_exp_f32_e32 v167, v167
	v_exp_f32_e32 v168, v168
	v_exp_f32_e32 v169, v169
	v_add_f32_e32 v162, 1.0, v162
	v_add_f32_e32 v163, 1.0, v163
	v_add_f32_e32 v164, 1.0, v164
	v_add_f32_e32 v165, 1.0, v165
	v_add_f32_e32 v166, 1.0, v166
	v_add_f32_e32 v167, 1.0, v167
	v_add_f32_e32 v168, 1.0, v168
	v_add_f32_e32 v169, 1.0, v169
	v_rcp_f32_e32 v162, v162
	v_rcp_f32_e32 v163, v163
	v_rcp_f32_e32 v164, v164
	v_rcp_f32_e32 v165, v165
	v_rcp_f32_e32 v166, v166
	v_rcp_f32_e32 v167, v167
	v_rcp_f32_e32 v168, v168
	v_rcp_f32_e32 v169, v169
	v_mul_f32_e32 v126, v126, v162
	v_mul_f32_e32 v127, v127, v163
	v_mul_f32_e32 v128, v128, v164
	v_mul_f32_e32 v129, v129, v165
	v_mul_f32_e32 v122, v122, v166
	v_mul_f32_e32 v123, v123, v167
	v_mul_f32_e32 v124, v124, v168
	v_mul_f32_e32 v125, v125, v169
	v_mul_f32_e32 v118, v126, v118
	v_mul_f32_e32 v119, v127, v119
	v_mul_f32_e32 v120, v128, v120
	v_mul_f32_e32 v121, v129, v121
	v_mul_f32_e32 v114, v122, v114
	v_mul_f32_e32 v115, v123, v115
	v_mul_f32_e32 v116, v124, v116
	v_mul_f32_e32 v117, v125, v117
	v_cvt_pk_bf16_f32 v178, v118, v119
	v_cvt_pk_bf16_f32 v179, v120, v121
	v_cvt_pk_bf16_f32 v180, v114, v115
	v_cvt_pk_bf16_f32 v181, v116, v117
	global_store_dwordx4 v[186:187], v[178:181], off
	v_lshl_add_u64 v[188:189], v[156:157], 0, v[138:139]
	v_mul_f32_e32 v170, 0xbfb8aa3b, v110
	v_mul_f32_e32 v171, 0xbfb8aa3b, v111
	v_mul_f32_e32 v172, 0xbfb8aa3b, v112
	v_mul_f32_e32 v173, 0xbfb8aa3b, v113
	v_mul_f32_e32 v174, 0xbfb8aa3b, v106
	v_mul_f32_e32 v175, 0xbfb8aa3b, v107
	v_mul_f32_e32 v176, 0xbfb8aa3b, v108
	v_mul_f32_e32 v177, 0xbfb8aa3b, v109
	v_exp_f32_e32 v170, v170
	v_exp_f32_e32 v171, v171
	v_exp_f32_e32 v172, v172
	v_exp_f32_e32 v173, v173
	v_exp_f32_e32 v174, v174
	v_exp_f32_e32 v175, v175
	v_exp_f32_e32 v176, v176
	v_exp_f32_e32 v177, v177
	v_add_f32_e32 v170, 1.0, v170
	v_add_f32_e32 v171, 1.0, v171
	v_add_f32_e32 v172, 1.0, v172
	v_add_f32_e32 v173, 1.0, v173
	v_add_f32_e32 v174, 1.0, v174
	v_add_f32_e32 v175, 1.0, v175
	v_add_f32_e32 v176, 1.0, v176
	v_add_f32_e32 v177, 1.0, v177
	v_rcp_f32_e32 v170, v170
	v_rcp_f32_e32 v171, v171
	v_rcp_f32_e32 v172, v172
	v_rcp_f32_e32 v173, v173
	v_rcp_f32_e32 v174, v174
	v_rcp_f32_e32 v175, v175
	v_rcp_f32_e32 v176, v176
	v_rcp_f32_e32 v177, v177
	v_mul_f32_e32 v110, v110, v170
	v_mul_f32_e32 v111, v111, v171
	v_mul_f32_e32 v112, v112, v172
	v_mul_f32_e32 v113, v113, v173
	v_mul_f32_e32 v106, v106, v174
	v_mul_f32_e32 v107, v107, v175
	v_mul_f32_e32 v108, v108, v176
	v_mul_f32_e32 v109, v109, v177
	v_mul_f32_e32 v102, v110, v102
	v_mul_f32_e32 v103, v111, v103
	v_mul_f32_e32 v104, v112, v104
	v_mul_f32_e32 v105, v113, v105
	v_mul_f32_e32 v98, v106, v98
	v_mul_f32_e32 v99, v107, v99
	v_mul_f32_e32 v100, v108, v100
	v_mul_f32_e32 v101, v109, v101
	v_cvt_pk_bf16_f32 v182, v102, v103
	v_cvt_pk_bf16_f32 v183, v104, v105
	v_cvt_pk_bf16_f32 v184, v98, v99
	v_cvt_pk_bf16_f32 v185, v100, v101
	global_store_dwordx4 v[188:189], v[182:185], off
	v_lshl_add_u64 v[186:187], v[156:157], 0, v[140:141]
	v_mul_f32_e32 v162, 0xbfb8aa3b, v94
	v_mul_f32_e32 v163, 0xbfb8aa3b, v95
	v_mul_f32_e32 v164, 0xbfb8aa3b, v96
	v_mul_f32_e32 v165, 0xbfb8aa3b, v97
	v_mul_f32_e32 v166, 0xbfb8aa3b, v90
	v_mul_f32_e32 v167, 0xbfb8aa3b, v91
	v_mul_f32_e32 v168, 0xbfb8aa3b, v92
	v_mul_f32_e32 v169, 0xbfb8aa3b, v93
	v_exp_f32_e32 v162, v162
	v_exp_f32_e32 v163, v163
	v_exp_f32_e32 v164, v164
	v_exp_f32_e32 v165, v165
	v_exp_f32_e32 v166, v166
	v_exp_f32_e32 v167, v167
	v_exp_f32_e32 v168, v168
	v_exp_f32_e32 v169, v169
	v_add_f32_e32 v162, 1.0, v162
	v_add_f32_e32 v163, 1.0, v163
	v_add_f32_e32 v164, 1.0, v164
	v_add_f32_e32 v165, 1.0, v165
	v_add_f32_e32 v166, 1.0, v166
	v_add_f32_e32 v167, 1.0, v167
	v_add_f32_e32 v168, 1.0, v168
	v_add_f32_e32 v169, 1.0, v169
	v_rcp_f32_e32 v162, v162
	v_rcp_f32_e32 v163, v163
	v_rcp_f32_e32 v164, v164
	v_rcp_f32_e32 v165, v165
	v_rcp_f32_e32 v166, v166
	v_rcp_f32_e32 v167, v167
	v_rcp_f32_e32 v168, v168
	v_rcp_f32_e32 v169, v169
	v_mul_f32_e32 v94, v94, v162
	v_mul_f32_e32 v95, v95, v163
	v_mul_f32_e32 v96, v96, v164
	v_mul_f32_e32 v97, v97, v165
	v_mul_f32_e32 v90, v90, v166
	v_mul_f32_e32 v91, v91, v167
	v_mul_f32_e32 v92, v92, v168
	v_mul_f32_e32 v93, v93, v169
	v_mul_f32_e32 v86, v94, v86
	v_mul_f32_e32 v87, v95, v87
	v_mul_f32_e32 v88, v96, v88
	v_mul_f32_e32 v89, v97, v89
	v_mul_f32_e32 v82, v90, v82
	v_mul_f32_e32 v83, v91, v83
	v_mul_f32_e32 v84, v92, v84
	v_mul_f32_e32 v85, v93, v85
	v_cvt_pk_bf16_f32 v178, v86, v87
	v_cvt_pk_bf16_f32 v179, v88, v89
	v_cvt_pk_bf16_f32 v180, v82, v83
	v_cvt_pk_bf16_f32 v181, v84, v85
	global_store_dwordx4 v[186:187], v[178:181], off
	v_lshl_add_u64 v[188:189], v[156:157], 0, v[142:143]
	v_mul_f32_e32 v170, 0xbfb8aa3b, v78
; __device__ __forceinline__ unsigned cvt_pk_bf16(float lo, float hi) { f32x2 v = {lo, hi}; bf16x2_t b = __builtin_convertvector(v, bf16x2_t); return __builtin_bit_cast(unsigned, b); }
; __device__ __forceinline__ float fast_exp2(float x) { return __builtin_amdgcn_exp2f(x); }
; __device__ __forceinline__ float fast_rcp(float x) { return __builtin_amdgcn_rcpf(x); }
;     __device__ __forceinline__ void operator()(ACC_T, const Unit& u, int wr, int wc, int fr, int fq) const {
;     ...
;             for (int m = 0; m < 4; ++m) { bf16_t* rowp = Hp + (size_t)(row0 + ai * HALF + m * 16) * DFF + col0; float r[8];
; #pragma unroll
;                 for (int n = 0; n < 2; ++n)
; #pragma unroll
;                     for (int e = 0; e < 4; ++e) { const float g = acc[ai][0][m][n][e], up = acc[ai][1][m][n][e]; r[n * 4 + e] = g * fast_rcp(1.f + fast_exp2(-g * LOG2E)) * up; }
;                 u32x4 w; w.x = cvt_pk_bf16(r[0], r[1]); w.y = cvt_pk_bf16(r[2], r[3]); w.z = cvt_pk_bf16(r[4], r[5]); w.w = cvt_pk_bf16(r[6], r[7]);
;                 *(u32x4*)rowp = w; }
	v_mul_f32_e32 v171, 0xbfb8aa3b, v79
	v_mul_f32_e32 v172, 0xbfb8aa3b, v80
	v_mul_f32_e32 v173, 0xbfb8aa3b, v81
	v_mul_f32_e32 v174, 0xbfb8aa3b, v74
	v_mul_f32_e32 v175, 0xbfb8aa3b, v75
	v_mul_f32_e32 v176, 0xbfb8aa3b, v76
	v_mul_f32_e32 v177, 0xbfb8aa3b, v77
	v_exp_f32_e32 v170, v170
	v_exp_f32_e32 v171, v171
	v_exp_f32_e32 v172, v172
	v_exp_f32_e32 v173, v173
	v_exp_f32_e32 v174, v174
	v_exp_f32_e32 v175, v175
	v_exp_f32_e32 v176, v176
	v_exp_f32_e32 v177, v177
	v_add_f32_e32 v170, 1.0, v170
	v_add_f32_e32 v171, 1.0, v171
	v_add_f32_e32 v172, 1.0, v172
	v_add_f32_e32 v173, 1.0, v173
	v_add_f32_e32 v174, 1.0, v174
	v_add_f32_e32 v175, 1.0, v175
	v_add_f32_e32 v176, 1.0, v176
	v_add_f32_e32 v177, 1.0, v177
	v_rcp_f32_e32 v170, v170
	v_rcp_f32_e32 v171, v171
	v_rcp_f32_e32 v172, v172
	v_rcp_f32_e32 v173, v173
	v_rcp_f32_e32 v174, v174
	v_rcp_f32_e32 v175, v175
	v_rcp_f32_e32 v176, v176
	v_rcp_f32_e32 v177, v177
	v_mul_f32_e32 v78, v78, v170
	v_mul_f32_e32 v79, v79, v171
	v_mul_f32_e32 v80, v80, v172
	v_mul_f32_e32 v81, v81, v173
	v_mul_f32_e32 v74, v74, v174
	v_mul_f32_e32 v75, v75, v175
	v_mul_f32_e32 v76, v76, v176
	v_mul_f32_e32 v77, v77, v177
	v_mul_f32_e32 v70, v78, v70
	v_mul_f32_e32 v71, v79, v71
	v_mul_f32_e32 v72, v80, v72
	v_mul_f32_e32 v73, v81, v73
	v_mul_f32_e32 v66, v74, v66
	v_mul_f32_e32 v67, v75, v67
	v_mul_f32_e32 v68, v76, v68
	v_mul_f32_e32 v69, v77, v69
	v_cvt_pk_bf16_f32 v182, v70, v71
	v_cvt_pk_bf16_f32 v183, v72, v73
	v_cvt_pk_bf16_f32 v184, v66, v67
	v_cvt_pk_bf16_f32 v185, v68, v69
	global_store_dwordx4 v[188:189], v[182:185], off
	v_lshl_add_u64 v[186:187], v[156:157], 0, v[144:145]
	v_mul_f32_e32 v162, 0xbfb8aa3b, v62
	v_mul_f32_e32 v163, 0xbfb8aa3b, v63
	v_mul_f32_e32 v164, 0xbfb8aa3b, v64
	v_mul_f32_e32 v165, 0xbfb8aa3b, v65
	v_mul_f32_e32 v166, 0xbfb8aa3b, v58
	v_mul_f32_e32 v167, 0xbfb8aa3b, v59
	v_mul_f32_e32 v168, 0xbfb8aa3b, v60
	v_mul_f32_e32 v169, 0xbfb8aa3b, v61
	v_exp_f32_e32 v162, v162
	v_exp_f32_e32 v163, v163
	v_exp_f32_e32 v164, v164
	v_exp_f32_e32 v165, v165
	v_exp_f32_e32 v166, v166
	v_exp_f32_e32 v167, v167
	v_exp_f32_e32 v168, v168
	v_exp_f32_e32 v169, v169
	v_add_f32_e32 v162, 1.0, v162
	v_add_f32_e32 v163, 1.0, v163
	v_add_f32_e32 v164, 1.0, v164
	v_add_f32_e32 v165, 1.0, v165
	v_add_f32_e32 v166, 1.0, v166
	v_add_f32_e32 v167, 1.0, v167
	v_add_f32_e32 v168, 1.0, v168
	v_add_f32_e32 v169, 1.0, v169
	v_rcp_f32_e32 v162, v162
	v_rcp_f32_e32 v163, v163
	v_rcp_f32_e32 v164, v164
	v_rcp_f32_e32 v165, v165
	v_rcp_f32_e32 v166, v166
	v_rcp_f32_e32 v167, v167
	v_rcp_f32_e32 v168, v168
	v_rcp_f32_e32 v169, v169
	v_mul_f32_e32 v62, v62, v162
	v_mul_f32_e32 v63, v63, v163
	v_mul_f32_e32 v64, v64, v164
	v_mul_f32_e32 v65, v65, v165
	v_mul_f32_e32 v58, v58, v166
	v_mul_f32_e32 v59, v59, v167
	v_mul_f32_e32 v60, v60, v168
	v_mul_f32_e32 v61, v61, v169
	v_mul_f32_e32 v54, v62, v54
	v_mul_f32_e32 v55, v63, v55
	v_mul_f32_e32 v56, v64, v56
	v_mul_f32_e32 v57, v65, v57
	v_mul_f32_e32 v50, v58, v50
	v_mul_f32_e32 v51, v59, v51
	v_mul_f32_e32 v52, v60, v52
	v_mul_f32_e32 v53, v61, v53
	v_cvt_pk_bf16_f32 v178, v54, v55
	v_cvt_pk_bf16_f32 v179, v56, v57
	v_cvt_pk_bf16_f32 v180, v50, v51
	v_cvt_pk_bf16_f32 v181, v52, v53
	global_store_dwordx4 v[186:187], v[178:181], off
	v_lshl_add_u64 v[188:189], v[156:157], 0, v[146:147]
	v_mul_f32_e32 v170, 0xbfb8aa3b, v46
	v_mul_f32_e32 v171, 0xbfb8aa3b, v47
	v_mul_f32_e32 v172, 0xbfb8aa3b, v48
	v_mul_f32_e32 v173, 0xbfb8aa3b, v49
	v_mul_f32_e32 v174, 0xbfb8aa3b, v42
	v_mul_f32_e32 v175, 0xbfb8aa3b, v43
	v_mul_f32_e32 v176, 0xbfb8aa3b, v44
	v_mul_f32_e32 v177, 0xbfb8aa3b, v45
	v_exp_f32_e32 v170, v170
	v_exp_f32_e32 v171, v171
	v_exp_f32_e32 v172, v172
	v_exp_f32_e32 v173, v173
	v_exp_f32_e32 v174, v174
	v_exp_f32_e32 v175, v175
	v_exp_f32_e32 v176, v176
	v_exp_f32_e32 v177, v177
	v_add_f32_e32 v170, 1.0, v170
	v_add_f32_e32 v171, 1.0, v171
	v_add_f32_e32 v172, 1.0, v172
	v_add_f32_e32 v173, 1.0, v173
	v_add_f32_e32 v174, 1.0, v174
	v_add_f32_e32 v175, 1.0, v175
	v_add_f32_e32 v176, 1.0, v176
	v_add_f32_e32 v177, 1.0, v177
	v_rcp_f32_e32 v170, v170
	v_rcp_f32_e32 v171, v171
	v_rcp_f32_e32 v172, v172
	v_rcp_f32_e32 v173, v173
	v_rcp_f32_e32 v174, v174
; __device__ __forceinline__ unsigned cvt_pk_bf16(float lo, float hi) { f32x2 v = {lo, hi}; bf16x2_t b = __builtin_convertvector(v, bf16x2_t); return __builtin_bit_cast(unsigned, b); }
; __device__ __forceinline__ float fast_exp2(float x) { return __builtin_amdgcn_exp2f(x); }
; __device__ __forceinline__ float fast_rcp(float x) { return __builtin_amdgcn_rcpf(x); }
; #define PG8_BAR __builtin_amdgcn_s_barrier()
;     __device__ __forceinline__ void operator()(ACC_T, const Unit& u, int wr, int wc, int fr, int fq) const {
;     ...
;             for (int m = 0; m < 4; ++m) { bf16_t* rowp = Hp + (size_t)(row0 + ai * HALF + m * 16) * DFF + col0; float r[8];
; #pragma unroll
;                 for (int n = 0; n < 2; ++n)
; #pragma unroll
;                     for (int e = 0; e < 4; ++e) { const float g = acc[ai][0][m][n][e], up = acc[ai][1][m][n][e]; r[n * 4 + e] = g * fast_rcp(1.f + fast_exp2(-g * LOG2E)) * up; }
;                 u32x4 w; w.x = cvt_pk_bf16(r[0], r[1]); w.y = cvt_pk_bf16(r[2], r[3]); w.z = cvt_pk_bf16(r[4], r[5]); w.w = cvt_pk_bf16(r[6], r[7]);
;                 *(u32x4*)rowp = w; }
; template <class Epi, bool ALIGN_EPI, bool ASLOT = false>
; __device__ __forceinline__ void gemm_phase(LAS unsigned char* lds, const Gemm g, const Sched& S, const Epi& E) {
;     ...
;         if constexpr (ALIGN_EPI) { if (wr == 0) PG8_BAR; }
;         E(acc, cur, wr, wc, fr, fq);
;         if (!has_next) break;
; #pragma unroll
;         for (int a = 0; a < 2; ++a)
; #pragma unroll
;             for (int b = 0; b < 2; ++b)
; #pragma unroll
;                 for (int m = 0; m < 4; ++m)
; #pragma unroll
;                     for (int n = 0; n < 2; ++n) acc[a][b][m][n] = (f32x4){0.f, 0.f, 0.f, 0.f};
;         cur = nxt; cA = nA; cB = nB; ++ui;
;         if constexpr (ALIGN_EPI) { if (wr == 1) PG8_BAR; }
	v_rcp_f32_e32 v175, v175
	v_rcp_f32_e32 v176, v176
	v_rcp_f32_e32 v177, v177
	v_mul_f32_e32 v46, v46, v170
	v_mul_f32_e32 v47, v47, v171
	v_mul_f32_e32 v48, v48, v172
	v_mul_f32_e32 v49, v49, v173
	v_mul_f32_e32 v42, v42, v174
	v_mul_f32_e32 v43, v43, v175
	v_mul_f32_e32 v44, v44, v176
	v_mul_f32_e32 v45, v45, v177
	v_mul_f32_e32 v38, v46, v38
	v_mul_f32_e32 v39, v47, v39
	v_mul_f32_e32 v40, v48, v40
	v_mul_f32_e32 v41, v49, v41
	v_mul_f32_e32 v34, v42, v34
	v_mul_f32_e32 v35, v43, v35
	v_mul_f32_e32 v36, v44, v36
	v_mul_f32_e32 v37, v45, v37
	v_cvt_pk_bf16_f32 v182, v38, v39
	v_cvt_pk_bf16_f32 v183, v40, v41
	v_cvt_pk_bf16_f32 v184, v34, v35
	v_cvt_pk_bf16_f32 v185, v36, v37
	global_store_dwordx4 v[188:189], v[182:185], off
	v_lshl_add_u64 v[186:187], v[156:157], 0, v[148:149]
	v_mul_f32_e32 v162, 0xbfb8aa3b, v30
	v_mul_f32_e32 v163, 0xbfb8aa3b, v31
	v_mul_f32_e32 v164, 0xbfb8aa3b, v32
	v_mul_f32_e32 v165, 0xbfb8aa3b, v33
	v_mul_f32_e32 v166, 0xbfb8aa3b, v26
	v_mul_f32_e32 v167, 0xbfb8aa3b, v27
	v_mul_f32_e32 v168, 0xbfb8aa3b, v28
	v_mul_f32_e32 v169, 0xbfb8aa3b, v29
	v_exp_f32_e32 v162, v162
	v_exp_f32_e32 v163, v163
	v_exp_f32_e32 v164, v164
	v_exp_f32_e32 v165, v165
	v_exp_f32_e32 v166, v166
	v_exp_f32_e32 v167, v167
	v_exp_f32_e32 v168, v168
	v_exp_f32_e32 v169, v169
	v_add_f32_e32 v162, 1.0, v162
	v_add_f32_e32 v163, 1.0, v163
	v_add_f32_e32 v164, 1.0, v164
	v_add_f32_e32 v165, 1.0, v165
	v_add_f32_e32 v166, 1.0, v166
	v_add_f32_e32 v167, 1.0, v167
	v_add_f32_e32 v168, 1.0, v168
	v_add_f32_e32 v169, 1.0, v169
	v_rcp_f32_e32 v162, v162
	v_rcp_f32_e32 v163, v163
	v_rcp_f32_e32 v164, v164
	v_rcp_f32_e32 v165, v165
	v_rcp_f32_e32 v166, v166
	v_rcp_f32_e32 v167, v167
	v_rcp_f32_e32 v168, v168
	v_rcp_f32_e32 v169, v169
	v_mul_f32_e32 v30, v30, v162
	v_mul_f32_e32 v31, v31, v163
	v_mul_f32_e32 v32, v32, v164
	v_mul_f32_e32 v33, v33, v165
	v_mul_f32_e32 v26, v26, v166
	v_mul_f32_e32 v27, v27, v167
	v_mul_f32_e32 v28, v28, v168
	v_mul_f32_e32 v29, v29, v169
	v_mul_f32_e32 v22, v30, v22
	v_mul_f32_e32 v23, v31, v23
	v_mul_f32_e32 v24, v32, v24
	v_mul_f32_e32 v25, v33, v25
	v_mul_f32_e32 v18, v26, v18
	v_mul_f32_e32 v19, v27, v19
	v_mul_f32_e32 v20, v28, v20
	v_mul_f32_e32 v21, v29, v21
	v_cvt_pk_bf16_f32 v178, v22, v23
	v_cvt_pk_bf16_f32 v179, v24, v25
	v_cvt_pk_bf16_f32 v180, v18, v19
	v_cvt_pk_bf16_f32 v181, v20, v21
	global_store_dwordx4 v[186:187], v[178:181], off
	v_lshl_add_u64 v[188:189], v[156:157], 0, v[150:151]
	v_mul_f32_e32 v170, 0xbfb8aa3b, v14
	v_mul_f32_e32 v171, 0xbfb8aa3b, v15
	v_mul_f32_e32 v172, 0xbfb8aa3b, v16
	v_mul_f32_e32 v173, 0xbfb8aa3b, v17
	v_mul_f32_e32 v174, 0xbfb8aa3b, v10
	v_mul_f32_e32 v175, 0xbfb8aa3b, v11
	v_mul_f32_e32 v176, 0xbfb8aa3b, v12
	v_mul_f32_e32 v177, 0xbfb8aa3b, v13
	v_exp_f32_e32 v170, v170
	v_exp_f32_e32 v171, v171
	v_exp_f32_e32 v172, v172
	v_exp_f32_e32 v173, v173
	v_exp_f32_e32 v174, v174
	v_exp_f32_e32 v175, v175
	v_exp_f32_e32 v176, v176
	v_exp_f32_e32 v177, v177
	v_add_f32_e32 v170, 1.0, v170
	v_add_f32_e32 v171, 1.0, v171
	v_add_f32_e32 v172, 1.0, v172
	v_add_f32_e32 v173, 1.0, v173
	v_add_f32_e32 v174, 1.0, v174
	v_add_f32_e32 v175, 1.0, v175
	v_add_f32_e32 v176, 1.0, v176
	v_add_f32_e32 v177, 1.0, v177
	v_rcp_f32_e32 v170, v170
	v_rcp_f32_e32 v171, v171
	v_rcp_f32_e32 v172, v172
	v_rcp_f32_e32 v173, v173
	v_rcp_f32_e32 v174, v174
	v_rcp_f32_e32 v175, v175
	v_rcp_f32_e32 v176, v176
	v_rcp_f32_e32 v177, v177
	v_mul_f32_e32 v14, v14, v170
	v_mul_f32_e32 v15, v15, v171
	v_mul_f32_e32 v16, v16, v172
	v_mul_f32_e32 v17, v17, v173
	v_mul_f32_e32 v10, v10, v174
	v_mul_f32_e32 v11, v11, v175
	v_mul_f32_e32 v12, v12, v176
	v_mul_f32_e32 v13, v13, v177
	v_mul_f32_e32 v6, v14, v6
	v_mul_f32_e32 v7, v15, v7
	v_mul_f32_e32 v8, v16, v8
	v_mul_f32_e32 v9, v17, v9
	v_mul_f32_e32 v2, v10, v2
	v_mul_f32_e32 v3, v11, v3
	v_mul_f32_e32 v4, v12, v4
	v_mul_f32_e32 v5, v13, v5
	v_cvt_pk_bf16_f32 v182, v6, v7
	v_cvt_pk_bf16_f32 v183, v8, v9
	v_cvt_pk_bf16_f32 v184, v2, v3
	v_cvt_pk_bf16_f32 v185, v4, v5
	global_store_dwordx4 v[188:189], v[182:185], off
	s_cbranch_vccnz .LBB0_849
	s_andn2_b64 vcc, exec, s[0:1]
	s_cbranch_vccnz .LBB0_848
	s_barrier
	s_branch .LBB0_848
